# grid barrier: non-leader workgroups poll the global release generation word instead of their XCD relay word (one hop shorter fan-out)
# baseline (speedup 1.0000x reference)
; __device__ __forceinline__ unsigned xb_ld(unsigned* p)              { return __hip_atomic_load(p, __ATOMIC_RELAXED, __HIP_MEMORY_SCOPE_AGENT); }
; __device__ __forceinline__ unsigned xb_add(unsigned* p, unsigned v) { return __hip_atomic_fetch_add(p, v, __ATOMIC_RELAXED, __HIP_MEMORY_SCOPE_AGENT); }
; #define XB_SPIN(cond, bar) do { unsigned _sp = 0; while (cond) { __builtin_amdgcn_s_sleep(1); \
;     if ((++_sp & 255u) == 0u) { if (xb_ld(&(bar)[XB_TMO])) break; if (_sp > XB_SPIN_CAP) { atomicAdd(&(bar)[XB_TMO], 1u); break; } } } } while (0)
; __device__ __forceinline__ void xcd_barrier(const XcdBarrier& b) {
;     ...
;         const unsigned old = xb_add(&bar[XB_XSUB(b.x)], 1u);
;         const unsigned gen = old / nloc;
;         if (old + 1u == (gen + 1u) * nloc) {
;             __builtin_amdgcn_fence(__ATOMIC_RELEASE, "agent");
;             asm volatile("s_waitcnt vmcnt(0)" ::: "memory");
;             const unsigned og = xb_add(&bar[XB_TOP], 1u);
;             const unsigned tg = og / nx;
;             if (og + 1u == (tg + 1u) * nx) xb_add(&bar[XB_TOPGEN], 1u);
;             else XB_SPIN(xb_ld(&bar[XB_TOPGEN]) == tg, bar);
;             __builtin_amdgcn_fence(__ATOMIC_ACQUIRE, "agent");
;             xb_add(&bar[XB_XGEN(b.x)], 1u);
;             asm volatile("s_waitcnt vmcnt(0)" ::: "memory");
;         } else {
;             XB_SPIN(xb_ld(&bar[XB_XGEN(b.x)]) == gen, bar);
.LBB0_51:
	s_or_b64 exec, exec, s[8:9]
	v_cvt_f32_u32_e32 v4, v2
	s_waitcnt vmcnt(0)
	v_readfirstlane_b32 s6, v3
	v_sub_u32_e32 v3, 0, v2
	v_rcp_iflag_f32_e32 v4, v4
	v_add_u32_e32 v5, s6, v1
	v_mul_f32_e32 v4, 0x4f7ffffe, v4
	v_cvt_u32_f32_e32 v4, v4
	v_mul_lo_u32 v1, v3, v4
	v_mul_hi_u32 v1, v4, v1
	v_add_u32_e32 v1, v4, v1
	v_mul_hi_u32 v1, v5, v1
	v_mul_lo_u32 v3, v1, v2
	v_sub_u32_e32 v3, v5, v3
	v_add_u32_e32 v4, 1, v1
	v_cmp_ge_u32_e32 vcc, v3, v2
	s_nop 1
	v_cndmask_b32_e32 v1, v1, v4, vcc
	v_sub_u32_e32 v4, v3, v2
	v_cndmask_b32_e32 v3, v3, v4, vcc
	v_add_u32_e32 v4, 1, v1
	v_cmp_ge_u32_e32 vcc, v3, v2
	v_add_u32_e32 v3, 1, v5
	s_nop 0
	v_cndmask_b32_e32 v1, v1, v4, vcc
	v_mul_lo_u32 v4, v2, v1
	v_add_u32_e32 v2, v4, v2
	v_cmp_ne_u32_e32 vcc, v3, v2
	s_and_saveexec_b64 s[6:7], vcc
	s_xor_b64 s[6:7], exec, s[6:7]
	s_cbranch_execz .LBB0_65
	s_waitcnt lgkmcnt(0)
	v_mov_b32_e32 v0, 0x603500
	global_load_dword v0, v0, s[68:69] sc1
	s_add_u32 s38, s68, 0x603500
	s_addc_u32 s39, s69, 0
	s_waitcnt vmcnt(0)
	v_cmp_eq_u32_e32 vcc, v0, v1
	s_and_saveexec_b64 s[8:9], vcc
	s_cbranch_execz .LBB0_64
	s_add_u32 s36, s68, 0x600200
	s_addc_u32 s37, s69, 0
	s_mov_b32 s24, 1
	s_mov_b64 s[40:41], 0
	v_mov_b32_e32 v0, 0
	s_branch .LBB0_55

; __device__ __forceinline__ unsigned xb_ld(unsigned* p)              { return __hip_atomic_load(p, __ATOMIC_RELAXED, __HIP_MEMORY_SCOPE_AGENT); }
; __device__ __forceinline__ unsigned xb_add(unsigned* p, unsigned v) { return __hip_atomic_fetch_add(p, v, __ATOMIC_RELAXED, __HIP_MEMORY_SCOPE_AGENT); }
; #define XB_SPIN(cond, bar) do { unsigned _sp = 0; while (cond) { __builtin_amdgcn_s_sleep(1); \
;     if ((++_sp & 255u) == 0u) { if (xb_ld(&(bar)[XB_TMO])) break; if (_sp > XB_SPIN_CAP) { atomicAdd(&(bar)[XB_TMO], 1u); break; } } } } while (0)
; __device__ __forceinline__ void xcd_barrier(const XcdBarrier& b) {
;     ...
;         const unsigned old = xb_add(&bar[XB_XSUB(b.x)], 1u);
;         const unsigned gen = old / nloc;
;         if (old + 1u == (gen + 1u) * nloc) {
;             __builtin_amdgcn_fence(__ATOMIC_RELEASE, "agent");
;             asm volatile("s_waitcnt vmcnt(0)" ::: "memory");
;             const unsigned og = xb_add(&bar[XB_TOP], 1u);
;             const unsigned tg = og / nx;
;             if (og + 1u == (tg + 1u) * nx) xb_add(&bar[XB_TOPGEN], 1u);
;             else XB_SPIN(xb_ld(&bar[XB_TOPGEN]) == tg, bar);
;             __builtin_amdgcn_fence(__ATOMIC_ACQUIRE, "agent");
;             xb_add(&bar[XB_XGEN(b.x)], 1u);
;             asm volatile("s_waitcnt vmcnt(0)" ::: "memory");
;         } else {
;             XB_SPIN(xb_ld(&bar[XB_XGEN(b.x)]) == gen, bar);
.LBB0_370:
	s_or_b64 exec, exec, s[36:37]
	v_cvt_f32_u32_e32 v4, v2
	s_waitcnt vmcnt(0)
	v_readfirstlane_b32 s2, v3
	v_sub_u32_e32 v3, 0, v2
	v_rcp_iflag_f32_e32 v4, v4
	v_add_u32_e32 v5, s2, v1
	v_mul_f32_e32 v4, 0x4f7ffffe, v4
	v_cvt_u32_f32_e32 v4, v4
	v_mul_lo_u32 v1, v3, v4
	v_mul_hi_u32 v1, v4, v1
	v_add_u32_e32 v1, v4, v1
	v_mul_hi_u32 v1, v5, v1
	v_mul_lo_u32 v3, v1, v2
	v_sub_u32_e32 v3, v5, v3
	v_add_u32_e32 v4, 1, v1
	v_cmp_ge_u32_e32 vcc, v3, v2
	s_nop 1
	v_cndmask_b32_e32 v1, v1, v4, vcc
	v_sub_u32_e32 v4, v3, v2
	v_cndmask_b32_e32 v3, v3, v4, vcc
	v_add_u32_e32 v4, 1, v1
	v_cmp_ge_u32_e32 vcc, v3, v2
	v_add_u32_e32 v3, 1, v5
	s_nop 0
	v_cndmask_b32_e32 v1, v1, v4, vcc
	v_mul_lo_u32 v4, v2, v1
	v_add_u32_e32 v2, v4, v2
	v_cmp_ne_u32_e32 vcc, v3, v2
	s_and_saveexec_b64 s[2:3], vcc
	s_xor_b64 s[8:9], exec, s[2:3]
	s_cbranch_execz .LBB0_384
	s_waitcnt lgkmcnt(0)
	v_mov_b32_e32 v0, 0x603500
	global_load_dword v0, v0, s[68:69] sc1
	s_add_u32 s40, s68, 0x603500
	s_addc_u32 s41, s69, 0
	s_waitcnt vmcnt(0)
	v_cmp_eq_u32_e32 vcc, v0, v1
	s_and_saveexec_b64 s[36:37], vcc
	s_cbranch_execz .LBB0_383
	s_add_u32 s38, s68, 0x600200
	s_addc_u32 s39, s69, 0
	s_mov_b32 s2, 1
	s_mov_b64 s[42:43], 0
	v_mov_b32_e32 v0, 0
	s_branch .LBB0_374

; __device__ __forceinline__ unsigned xb_ld(unsigned* p)              { return __hip_atomic_load(p, __ATOMIC_RELAXED, __HIP_MEMORY_SCOPE_AGENT); }
; __device__ __forceinline__ unsigned xb_add(unsigned* p, unsigned v) { return __hip_atomic_fetch_add(p, v, __ATOMIC_RELAXED, __HIP_MEMORY_SCOPE_AGENT); }
; #define XB_SPIN(cond, bar) do { unsigned _sp = 0; while (cond) { __builtin_amdgcn_s_sleep(1); \
;     if ((++_sp & 255u) == 0u) { if (xb_ld(&(bar)[XB_TMO])) break; if (_sp > XB_SPIN_CAP) { atomicAdd(&(bar)[XB_TMO], 1u); break; } } } } while (0)
; __device__ __forceinline__ void xcd_barrier(const XcdBarrier& b) {
;     ...
;         const unsigned old = xb_add(&bar[XB_XSUB(b.x)], 1u);
;         const unsigned gen = old / nloc;
;         if (old + 1u == (gen + 1u) * nloc) {
;             __builtin_amdgcn_fence(__ATOMIC_RELEASE, "agent");
;             asm volatile("s_waitcnt vmcnt(0)" ::: "memory");
;             const unsigned og = xb_add(&bar[XB_TOP], 1u);
;             const unsigned tg = og / nx;
;             if (og + 1u == (tg + 1u) * nx) xb_add(&bar[XB_TOPGEN], 1u);
;             else XB_SPIN(xb_ld(&bar[XB_TOPGEN]) == tg, bar);
;             __builtin_amdgcn_fence(__ATOMIC_ACQUIRE, "agent");
;             xb_add(&bar[XB_XGEN(b.x)], 1u);
;             asm volatile("s_waitcnt vmcnt(0)" ::: "memory");
;         } else {
;             XB_SPIN(xb_ld(&bar[XB_XGEN(b.x)]) == gen, bar);
.LBB0_514:
	s_or_b64 exec, exec, s[10:11]
	v_cvt_f32_u32_e32 v4, v2
	s_waitcnt vmcnt(0)
	v_readfirstlane_b32 s2, v3
	v_sub_u32_e32 v3, 0, v2
	v_rcp_iflag_f32_e32 v4, v4
	v_add_u32_e32 v5, s2, v1
	v_mul_f32_e32 v4, 0x4f7ffffe, v4
	v_cvt_u32_f32_e32 v4, v4
	v_mul_lo_u32 v1, v3, v4
	v_mul_hi_u32 v1, v4, v1
	v_add_u32_e32 v1, v4, v1
	v_mul_hi_u32 v1, v5, v1
	v_mul_lo_u32 v3, v1, v2
	v_sub_u32_e32 v3, v5, v3
	v_add_u32_e32 v4, 1, v1
	v_cmp_ge_u32_e32 vcc, v3, v2
	s_nop 1
	v_cndmask_b32_e32 v1, v1, v4, vcc
	v_sub_u32_e32 v4, v3, v2
	v_cndmask_b32_e32 v3, v3, v4, vcc
	v_add_u32_e32 v4, 1, v1
	v_cmp_ge_u32_e32 vcc, v3, v2
	v_add_u32_e32 v3, 1, v5
	s_nop 0
	v_cndmask_b32_e32 v1, v1, v4, vcc
	v_mul_lo_u32 v4, v2, v1
	v_add_u32_e32 v2, v4, v2
	v_cmp_ne_u32_e32 vcc, v3, v2
	s_and_saveexec_b64 s[2:3], vcc
	s_xor_b64 s[8:9], exec, s[2:3]
	s_cbranch_execz .LBB0_528
	s_waitcnt lgkmcnt(0)
	v_mov_b32_e32 v0, 0x603500
	global_load_dword v0, v0, s[68:69] sc1
	s_add_u32 s14, s68, 0x603500
	s_addc_u32 s15, s69, 0
	s_waitcnt vmcnt(0)
	v_cmp_eq_u32_e32 vcc, v0, v1
	s_and_saveexec_b64 s[10:11], vcc
	s_cbranch_execz .LBB0_527
	s_add_u32 s12, s68, 0x600200
	s_addc_u32 s13, s69, 0
	s_mov_b32 s2, 1
	s_mov_b64 s[16:17], 0
	v_mov_b32_e32 v0, 0
	s_branch .LBB0_518

; __device__ __forceinline__ unsigned xb_ld(unsigned* p)              { return __hip_atomic_load(p, __ATOMIC_RELAXED, __HIP_MEMORY_SCOPE_AGENT); }
; __device__ __forceinline__ unsigned xb_add(unsigned* p, unsigned v) { return __hip_atomic_fetch_add(p, v, __ATOMIC_RELAXED, __HIP_MEMORY_SCOPE_AGENT); }
; #define XB_SPIN(cond, bar) do { unsigned _sp = 0; while (cond) { __builtin_amdgcn_s_sleep(1); \
;     if ((++_sp & 255u) == 0u) { if (xb_ld(&(bar)[XB_TMO])) break; if (_sp > XB_SPIN_CAP) { atomicAdd(&(bar)[XB_TMO], 1u); break; } } } } while (0)
; __device__ __forceinline__ void xcd_barrier(const XcdBarrier& b) {
;     ...
;         const unsigned old = xb_add(&bar[XB_XSUB(b.x)], 1u);
;         const unsigned gen = old / nloc;
;         if (old + 1u == (gen + 1u) * nloc) {
;             __builtin_amdgcn_fence(__ATOMIC_RELEASE, "agent");
;             asm volatile("s_waitcnt vmcnt(0)" ::: "memory");
;             const unsigned og = xb_add(&bar[XB_TOP], 1u);
;             const unsigned tg = og / nx;
;             if (og + 1u == (tg + 1u) * nx) xb_add(&bar[XB_TOPGEN], 1u);
;             else XB_SPIN(xb_ld(&bar[XB_TOPGEN]) == tg, bar);
;             __builtin_amdgcn_fence(__ATOMIC_ACQUIRE, "agent");
;             xb_add(&bar[XB_XGEN(b.x)], 1u);
;             asm volatile("s_waitcnt vmcnt(0)" ::: "memory");
;         } else {
;             XB_SPIN(xb_ld(&bar[XB_XGEN(b.x)]) == gen, bar);
.LBB0_597:
	s_or_b64 exec, exec, s[8:9]
	v_cvt_f32_u32_e32 v4, v2
	s_waitcnt vmcnt(0)
	v_readfirstlane_b32 s6, v3
	v_sub_u32_e32 v3, 0, v2
	v_rcp_iflag_f32_e32 v4, v4
	v_add_u32_e32 v5, s6, v1
	v_mul_f32_e32 v4, 0x4f7ffffe, v4
	v_cvt_u32_f32_e32 v4, v4
	v_mul_lo_u32 v1, v3, v4
	v_mul_hi_u32 v1, v4, v1
	v_add_u32_e32 v1, v4, v1
	v_mul_hi_u32 v1, v5, v1
	v_mul_lo_u32 v3, v1, v2
	v_sub_u32_e32 v3, v5, v3
	v_add_u32_e32 v4, 1, v1
	v_cmp_ge_u32_e32 vcc, v3, v2
	s_nop 1
	v_cndmask_b32_e32 v1, v1, v4, vcc
	v_sub_u32_e32 v4, v3, v2
	v_cndmask_b32_e32 v3, v3, v4, vcc
	v_add_u32_e32 v4, 1, v1
	v_cmp_ge_u32_e32 vcc, v3, v2
	v_add_u32_e32 v3, 1, v5
	s_nop 0
	v_cndmask_b32_e32 v1, v1, v4, vcc
	v_mul_lo_u32 v4, v2, v1
	v_add_u32_e32 v2, v4, v2
	v_cmp_ne_u32_e32 vcc, v3, v2
	s_and_saveexec_b64 s[6:7], vcc
	s_xor_b64 s[6:7], exec, s[6:7]
	s_cbranch_execz .LBB0_611
	s_waitcnt lgkmcnt(0)
	v_mov_b32_e32 v0, 0x603500
	global_load_dword v0, v0, s[68:69] sc1
	s_add_u32 s12, s68, 0x603500
	s_addc_u32 s13, s69, 0
	s_waitcnt vmcnt(0)
	v_cmp_eq_u32_e32 vcc, v0, v1
	s_and_saveexec_b64 s[8:9], vcc
	s_cbranch_execz .LBB0_610
	s_add_u32 s10, s68, 0x600200
	s_addc_u32 s11, s69, 0
	s_mov_b32 s24, 1
	s_mov_b64 s[14:15], 0
	v_mov_b32_e32 v0, 0
	s_branch .LBB0_601

; __device__ __forceinline__ unsigned xb_ld(unsigned* p)              { return __hip_atomic_load(p, __ATOMIC_RELAXED, __HIP_MEMORY_SCOPE_AGENT); }
; __device__ __forceinline__ unsigned xb_add(unsigned* p, unsigned v) { return __hip_atomic_fetch_add(p, v, __ATOMIC_RELAXED, __HIP_MEMORY_SCOPE_AGENT); }
; #define XB_SPIN(cond, bar) do { unsigned _sp = 0; while (cond) { __builtin_amdgcn_s_sleep(1); \
;     if ((++_sp & 255u) == 0u) { if (xb_ld(&(bar)[XB_TMO])) break; if (_sp > XB_SPIN_CAP) { atomicAdd(&(bar)[XB_TMO], 1u); break; } } } } while (0)
; __device__ __forceinline__ void xcd_barrier(const XcdBarrier& b) {
;     ...
;         const unsigned old = xb_add(&bar[XB_XSUB(b.x)], 1u);
;         const unsigned gen = old / nloc;
;         if (old + 1u == (gen + 1u) * nloc) {
;             __builtin_amdgcn_fence(__ATOMIC_RELEASE, "agent");
;             asm volatile("s_waitcnt vmcnt(0)" ::: "memory");
;             const unsigned og = xb_add(&bar[XB_TOP], 1u);
;             const unsigned tg = og / nx;
;             if (og + 1u == (tg + 1u) * nx) xb_add(&bar[XB_TOPGEN], 1u);
;             else XB_SPIN(xb_ld(&bar[XB_TOPGEN]) == tg, bar);
;             __builtin_amdgcn_fence(__ATOMIC_ACQUIRE, "agent");
;             xb_add(&bar[XB_XGEN(b.x)], 1u);
;             asm volatile("s_waitcnt vmcnt(0)" ::: "memory");
;         } else {
;             XB_SPIN(xb_ld(&bar[XB_XGEN(b.x)]) == gen, bar);
.LBB0_741:
	s_or_b64 exec, exec, s[10:11]
	v_cvt_f32_u32_e32 v4, v2
	s_waitcnt vmcnt(0)
	v_readfirstlane_b32 s8, v3
	v_sub_u32_e32 v3, 0, v2
	v_rcp_iflag_f32_e32 v4, v4
	v_add_u32_e32 v5, s8, v1
	v_mul_f32_e32 v4, 0x4f7ffffe, v4
	v_cvt_u32_f32_e32 v4, v4
	v_mul_lo_u32 v1, v3, v4
	v_mul_hi_u32 v1, v4, v1
	v_add_u32_e32 v1, v4, v1
	v_mul_hi_u32 v1, v5, v1
	v_mul_lo_u32 v3, v1, v2
	v_sub_u32_e32 v3, v5, v3
	v_add_u32_e32 v4, 1, v1
	v_cmp_ge_u32_e32 vcc, v3, v2
	s_nop 1
	v_cndmask_b32_e32 v1, v1, v4, vcc
	v_sub_u32_e32 v4, v3, v2
	v_cndmask_b32_e32 v3, v3, v4, vcc
	v_add_u32_e32 v4, 1, v1
	v_cmp_ge_u32_e32 vcc, v3, v2
	v_add_u32_e32 v3, 1, v5
	s_nop 0
	v_cndmask_b32_e32 v1, v1, v4, vcc
	v_mul_lo_u32 v4, v2, v1
	v_add_u32_e32 v2, v4, v2
	v_cmp_ne_u32_e32 vcc, v3, v2
	s_and_saveexec_b64 s[8:9], vcc
	s_xor_b64 s[8:9], exec, s[8:9]
	s_cbranch_execz .LBB0_755
	s_waitcnt lgkmcnt(0)
	v_mov_b32_e32 v0, 0x603500
	global_load_dword v0, v0, s[68:69] sc1
	s_add_u32 s14, s68, 0x603500
	s_addc_u32 s15, s69, 0
	s_waitcnt vmcnt(0)
	v_cmp_eq_u32_e32 vcc, v0, v1
	s_and_saveexec_b64 s[10:11], vcc
	s_cbranch_execz .LBB0_754
	s_add_u32 s12, s68, 0x600200
	s_addc_u32 s13, s69, 0
	s_mov_b32 s26, 1
	s_mov_b64 s[16:17], 0
	v_mov_b32_e32 v0, 0
	s_branch .LBB0_745

; __device__ __forceinline__ unsigned xb_ld(unsigned* p)              { return __hip_atomic_load(p, __ATOMIC_RELAXED, __HIP_MEMORY_SCOPE_AGENT); }
; __device__ __forceinline__ unsigned xb_add(unsigned* p, unsigned v) { return __hip_atomic_fetch_add(p, v, __ATOMIC_RELAXED, __HIP_MEMORY_SCOPE_AGENT); }
; #define XB_SPIN(cond, bar) do { unsigned _sp = 0; while (cond) { __builtin_amdgcn_s_sleep(1); \
;     if ((++_sp & 255u) == 0u) { if (xb_ld(&(bar)[XB_TMO])) break; if (_sp > XB_SPIN_CAP) { atomicAdd(&(bar)[XB_TMO], 1u); break; } } } } while (0)
; __device__ __forceinline__ void xcd_barrier(const XcdBarrier& b) {
;     ...
;         const unsigned old = xb_add(&bar[XB_XSUB(b.x)], 1u);
;         const unsigned gen = old / nloc;
;         if (old + 1u == (gen + 1u) * nloc) {
;             __builtin_amdgcn_fence(__ATOMIC_RELEASE, "agent");
;             asm volatile("s_waitcnt vmcnt(0)" ::: "memory");
;             const unsigned og = xb_add(&bar[XB_TOP], 1u);
;             const unsigned tg = og / nx;
;             if (og + 1u == (tg + 1u) * nx) xb_add(&bar[XB_TOPGEN], 1u);
;             else XB_SPIN(xb_ld(&bar[XB_TOPGEN]) == tg, bar);
;             __builtin_amdgcn_fence(__ATOMIC_ACQUIRE, "agent");
;             xb_add(&bar[XB_XGEN(b.x)], 1u);
;             asm volatile("s_waitcnt vmcnt(0)" ::: "memory");
;         } else {
;             XB_SPIN(xb_ld(&bar[XB_XGEN(b.x)]) == gen, bar);
.LBB0_834:
	s_or_b64 exec, exec, s[12:13]
	v_cvt_f32_u32_e32 v4, v2
	s_waitcnt vmcnt(0)
	v_readfirstlane_b32 s10, v3
	v_sub_u32_e32 v3, 0, v2
	v_rcp_iflag_f32_e32 v4, v4
	v_add_u32_e32 v5, s10, v1
	v_mul_f32_e32 v4, 0x4f7ffffe, v4
	v_cvt_u32_f32_e32 v4, v4
	v_mul_lo_u32 v1, v3, v4
	v_mul_hi_u32 v1, v4, v1
	v_add_u32_e32 v1, v4, v1
	v_mul_hi_u32 v1, v5, v1
	v_mul_lo_u32 v3, v1, v2
	v_sub_u32_e32 v3, v5, v3
	v_add_u32_e32 v4, 1, v1
	v_cmp_ge_u32_e32 vcc, v3, v2
	s_nop 1
	v_cndmask_b32_e32 v1, v1, v4, vcc
	v_sub_u32_e32 v4, v3, v2
	v_cndmask_b32_e32 v3, v3, v4, vcc
	v_add_u32_e32 v4, 1, v1
	v_cmp_ge_u32_e32 vcc, v3, v2
	v_add_u32_e32 v3, 1, v5
	s_nop 0
	v_cndmask_b32_e32 v1, v1, v4, vcc
	v_mul_lo_u32 v4, v2, v1
	v_add_u32_e32 v2, v4, v2
	v_cmp_ne_u32_e32 vcc, v3, v2
	s_and_saveexec_b64 s[10:11], vcc
	s_xor_b64 s[10:11], exec, s[10:11]
	s_cbranch_execz .LBB0_848
	s_waitcnt lgkmcnt(0)
	v_mov_b32_e32 v0, 0x603500
	global_load_dword v0, v0, s[68:69] sc1
	s_add_u32 s16, s68, 0x603500
	s_addc_u32 s17, s69, 0
	s_waitcnt vmcnt(0)
	v_cmp_eq_u32_e32 vcc, v0, v1
	s_and_saveexec_b64 s[12:13], vcc
	s_cbranch_execz .LBB0_847
	s_add_u32 s14, s68, 0x600200
	s_addc_u32 s15, s69, 0
	s_mov_b32 s28, 1
	s_mov_b64 s[18:19], 0
	v_mov_b32_e32 v0, 0
	s_branch .LBB0_838
